# grid barrier: L1 invalidate issued by thread 0 right after its arrival atomics so it overlaps the poll wait
# speedup vs baseline: 1.0655x; 1.0078x over previous
.Lmy_xb_poll:
	s_mov_b64 exec, s[14:15]
	s_mov_b32 s3, 0
	buffer_inv sc1

.Lmy_xb_done:
	s_waitcnt vmcnt(0)
	s_branch .LBB0_10
